# v71 + G2 epilogue: rope-B table staged in spare LDS, per-fragment table loads are ds_read_b128
# speedup vs baseline: 1.0019x; 1.0019x over previous
.LBB0_345:
	s_and_b64 vcc, exec, s[36:37]
	s_cbranch_vccz .LBB0_564
	v_readlane_b32 s2, v254, 52
	v_readlane_b32 s3, v254, 53
	v_lshlrev_b32_e32 v44, 4, v168
	v_add_u32_e32 v45, 0x2000, v44
	s_nop 4
	global_load_dwordx4 v[46:49], v45, s[2:3]
	v_add_u32_e32 v45, 0x10000, v44
	s_waitcnt vmcnt(0)
	ds_write_b128 v45, v[46:49]
	s_waitcnt lgkmcnt(0)
	s_barrier
	v_readlane_b32 s2, v253, 13
	v_readlane_b32 s3, v253, 14
	s_andn2_b64 vcc, exec, s[2:3]
	v_readlane_b32 s2, v250, 0
	s_mov_b32 s40, s2
	s_cbranch_vccz .LBB0_397

.LBB0_501:
	v_and_b32_e32 v70, 15, v3
	v_bfe_u32 v72, v3, 4, 2
	s_lshl_b32 s20, s40, 7
	s_and_b32 s2, s42, 64
	s_lshl_b32 s3, s41, 7
	s_or_b32 s46, s2, s20
	s_ashr_i32 s2, s42, 1
	s_and_b32 s20, s2, 0xffffffc0
	s_mul_hi_i32 s2, s46, 0x2aaaaaab
	s_add_i32 s20, s20, s3
	s_lshr_b32 s3, s2, 31
	s_lshr_b32 s2, s2, 4
	s_add_i32 s2, s2, s3
	s_mulk_i32 s2, 0x60
	s_bfe_u32 s53, s20, 0x50006
	s_sub_i32 s2, s46, s2
	s_cmp_gt_i32 s2, 63
	s_cselect_b64 s[42:43], -1, 0
	s_cmp_eq_u32 s2, 64
	v_lshrrev_b32_e32 v0, 2, v3
	s_cselect_b64 s[38:39], -1, 0
	s_cmp_lt_i32 s2, 64
	v_or_b32_e32 v71, s20, v70
	s_mov_b32 s2, 0x3e16c740
	s_movk_i32 s1, 0xfff
	v_cmp_lt_u32_e64 s[36:37], 1, v72
	v_and_b32_e32 v3, 4, v0
	v_pk_mul_f32 v[0:1], v[66:67], s[2:3] op_sel_hi:[1,0]
	v_pk_mul_f32 v[66:67], v[64:65], s[2:3] op_sel_hi:[1,0]
	v_cmp_lt_i32_e32 vcc, s1, v71
	s_cbranch_scc1 .LBB0_505
	v_cmp_lt_i32_e64 s[40:41], v180, v182
	s_nop 1
	v_cndmask_b32_e64 v64, v179, v180, s[40:41]
	v_lshlrev_b32_e32 v65, 2, v64
	ds_bpermute_b32 v68, v65, v66
	ds_bpermute_b32 v69, v65, v67
	ds_bpermute_b32 v64, v65, v0
	ds_bpermute_b32 v65, v65, v1
	s_and_saveexec_b64 s[40:41], vcc
	s_cbranch_execz .LBB0_504
	v_mov_b32_e32 v73, s53
	v_cndmask_b32_e64 v73, v70, v73, s[38:39]
	v_lshlrev_b32_e32 v74, 2, v3
	v_readlane_b32 s56, v254, 48
	v_lshl_or_b32 v74, v73, 5, v74
	v_mov_b32_e32 v75, v2
	v_readlane_b32 s60, v254, 52
	v_readlane_b32 s61, v254, 53
	v_readlane_b32 s57, v254, 49
	v_readlane_b32 s58, v254, 50
	v_lshl_add_u64 v[74:75], s[60:61], 0, v[74:75]
	v_add_co_u32_e32 v78, vcc, 0x2000, v74
	v_readlane_b32 s59, v254, 51
	s_nop 0
	v_addc_co_u32_e32 v79, vcc, 0, v75, vcc
	v_subrev_u32_e32 v130, s60, v78
	v_add_u32_e32 v130, 0xe000, v130
	ds_read_b128 v[74:77], v130 offset:2048
	s_nop 0
	ds_read_b128 v[78:81], v130
	v_readlane_b32 s62, v254, 54
	v_readlane_b32 s63, v254, 55
	s_waitcnt lgkmcnt(0)
	v_pk_mul_f32 v[68:69], v[74:75], v[68:69]
	v_pk_mul_f32 v[64:65], v[76:77], v[64:65]
	v_cndmask_b32_e64 v69, -v69, v69, s[36:37]
	v_cndmask_b32_e64 v65, -v65, v65, s[36:37]
	v_cndmask_b32_e64 v64, -v64, v64, s[36:37]
	v_cndmask_b32_e64 v68, -v68, v68, s[36:37]
	v_pk_fma_f32 v[0:1], v[0:1], v[80:81], v[64:65]
	v_pk_fma_f32 v[66:67], v[66:67], v[78:79], v[68:69]

.LBB0_505:
	v_readlane_b32 s2, v252, 32
	s_waitcnt lgkmcnt(0)
	v_lshlrev_b32_e32 v64, 3, v72
	v_mov_b32_e32 v65, v2
	v_readlane_b32 s3, v252, 33
	s_ashr_i32 s47, s46, 31
	s_movk_i32 s1, 0x600
	v_lshl_add_u64 v[64:65], s[2:3], 0, v[64:65]
	v_lshl_add_u64 v[64:65], s[46:47], 1, v[64:65]
	v_cvt_pk_bf16_f32 v66, v66, v67
	v_cvt_pk_bf16_f32 v67, v0, v1
	v_mad_i64_i32 v[0:1], s[40:41], v71, s1, v[64:65]
	v_or_b32_e32 v72, 16, v70
	global_store_dwordx2 v[0:1], v[66:67], off
	v_or_b32_e32 v73, s20, v72
	s_mov_b32 s2, 0x3e16c740
	v_cndmask_b32_e64 v66, 0, 1, s[42:43]
	s_movk_i32 s1, 0xfff
	v_pk_mul_f32 v[62:63], v[62:63], s[2:3] op_sel_hi:[1,0]
	v_pk_mul_f32 v[60:61], v[60:61], s[2:3] op_sel_hi:[1,0]
	v_cmp_ne_u32_e64 s[40:41], 1, v66
	s_andn2_b64 vcc, exec, s[42:43]
	v_cmp_lt_i32_e64 s[42:43], s1, v73
	s_cbranch_vccnz .LBB0_509
	v_cmp_lt_i32_e32 vcc, v180, v182
	s_nop 1
	v_cndmask_b32_e32 v66, v179, v180, vcc
	v_lshlrev_b32_e32 v67, 2, v66
	ds_bpermute_b32 v68, v67, v60
	ds_bpermute_b32 v69, v67, v61
	ds_bpermute_b32 v66, v67, v62
	ds_bpermute_b32 v67, v67, v63
	s_and_saveexec_b64 s[48:49], s[42:43]
	s_cbranch_execz .LBB0_508
	v_mov_b32_e32 v74, s53
	v_cndmask_b32_e64 v74, v72, v74, s[38:39]
	v_lshlrev_b32_e32 v75, 2, v3
	v_readlane_b32 s56, v254, 48
	v_lshl_or_b32 v74, v74, 5, v75
	v_mov_b32_e32 v75, v2
	v_readlane_b32 s60, v254, 52
	v_readlane_b32 s61, v254, 53
	v_readlane_b32 s57, v254, 49
	v_readlane_b32 s58, v254, 50
	v_lshl_add_u64 v[74:75], s[60:61], 0, v[74:75]
	v_add_co_u32_e32 v78, vcc, 0x2000, v74
	v_readlane_b32 s59, v254, 51
	s_nop 0
	v_addc_co_u32_e32 v79, vcc, 0, v75, vcc
	v_subrev_u32_e32 v130, s60, v78
	v_add_u32_e32 v130, 0xe000, v130
	ds_read_b128 v[74:77], v130 offset:2048
	s_nop 0
	ds_read_b128 v[78:81], v130
	v_readlane_b32 s62, v254, 54
	v_readlane_b32 s63, v254, 55
	s_waitcnt lgkmcnt(0)
	v_pk_mul_f32 v[68:69], v[74:75], v[68:69]
	v_pk_mul_f32 v[66:67], v[76:77], v[66:67]
	v_cndmask_b32_e64 v69, -v69, v69, s[36:37]
	v_cndmask_b32_e64 v67, -v67, v67, s[36:37]
	v_cndmask_b32_e64 v66, -v66, v66, s[36:37]
	v_cndmask_b32_e64 v68, -v68, v68, s[36:37]
	v_pk_fma_f32 v[62:63], v[62:63], v[80:81], v[66:67]
	v_pk_fma_f32 v[60:61], v[60:61], v[78:79], v[68:69]

.LBB0_509:
	s_movk_i32 s1, 0x600
	s_waitcnt lgkmcnt(0)
	v_or_b32_e32 v68, 32, v70
	v_cvt_pk_bf16_f32 v66, v60, v61
	v_mad_i64_i32 v[60:61], s[42:43], v73, s1, v[64:65]
	v_or_b32_e32 v69, s20, v68
	s_movk_i32 s1, 0xfff
	v_cvt_pk_bf16_f32 v67, v62, v63
	v_pk_mul_f32 v[58:59], v[58:59], s[2:3] op_sel_hi:[1,0]
	v_pk_mul_f32 v[56:57], v[56:57], s[2:3] op_sel_hi:[1,0]
	s_and_b64 vcc, exec, s[40:41]
	v_cmp_lt_i32_e64 s[42:43], s1, v69
	global_store_dwordx2 v[60:61], v[66:67], off
	s_cbranch_vccnz .LBB0_513
	v_cmp_lt_i32_e32 vcc, v180, v182
	s_nop 1
	v_cndmask_b32_e32 v62, v179, v180, vcc
	v_lshlrev_b32_e32 v63, 2, v62
	ds_bpermute_b32 v66, v63, v56
	ds_bpermute_b32 v67, v63, v57
	ds_bpermute_b32 v62, v63, v58
	ds_bpermute_b32 v63, v63, v59
	s_and_saveexec_b64 s[48:49], s[42:43]
	s_cbranch_execz .LBB0_512
	v_mov_b32_e32 v74, s53
	v_cndmask_b32_e64 v74, v68, v74, s[38:39]
	v_lshlrev_b32_e32 v75, 2, v3
	v_readlane_b32 s56, v254, 48
	v_lshl_or_b32 v74, v74, 5, v75
	v_mov_b32_e32 v75, v2
	v_readlane_b32 s60, v254, 52
	v_readlane_b32 s61, v254, 53
	v_readlane_b32 s57, v254, 49
	v_readlane_b32 s58, v254, 50
	v_lshl_add_u64 v[74:75], s[60:61], 0, v[74:75]
	v_add_co_u32_e32 v78, vcc, 0x2000, v74
	v_readlane_b32 s59, v254, 51
	s_nop 0
	v_addc_co_u32_e32 v79, vcc, 0, v75, vcc
	v_subrev_u32_e32 v130, s60, v78
	v_add_u32_e32 v130, 0xe000, v130
	ds_read_b128 v[74:77], v130 offset:2048
	s_nop 0
	ds_read_b128 v[78:81], v130
	v_readlane_b32 s62, v254, 54
	v_readlane_b32 s63, v254, 55
	s_waitcnt lgkmcnt(0)
	v_pk_mul_f32 v[66:67], v[74:75], v[66:67]
	v_pk_mul_f32 v[62:63], v[76:77], v[62:63]
	v_cndmask_b32_e64 v67, -v67, v67, s[36:37]
	v_cndmask_b32_e64 v63, -v63, v63, s[36:37]
	v_cndmask_b32_e64 v62, -v62, v62, s[36:37]
	v_cndmask_b32_e64 v66, -v66, v66, s[36:37]
	v_pk_fma_f32 v[58:59], v[58:59], v[80:81], v[62:63]
	v_pk_fma_f32 v[56:57], v[56:57], v[78:79], v[66:67]

.LBB0_513:
	s_movk_i32 s1, 0x600
	s_waitcnt lgkmcnt(0)
	v_or_b32_e32 v66, 48, v70
	v_cvt_pk_bf16_f32 v62, v56, v57
	v_mad_i64_i32 v[56:57], s[42:43], v69, s1, v[64:65]
	v_or_b32_e32 v67, s20, v66
	s_movk_i32 s1, 0xfff
	v_cvt_pk_bf16_f32 v63, v58, v59
	v_pk_mul_f32 v[54:55], v[54:55], s[2:3] op_sel_hi:[1,0]
	v_pk_mul_f32 v[52:53], v[52:53], s[2:3] op_sel_hi:[1,0]
	s_and_b64 vcc, exec, s[40:41]
	v_cmp_lt_i32_e64 s[40:41], s1, v67
	global_store_dwordx2 v[56:57], v[62:63], off
	s_cbranch_vccnz .LBB0_517
	v_cmp_lt_i32_e32 vcc, v180, v182
	s_nop 1
	v_cndmask_b32_e32 v58, v179, v180, vcc
	v_lshlrev_b32_e32 v59, 2, v58
	ds_bpermute_b32 v62, v59, v52
	ds_bpermute_b32 v63, v59, v53
	ds_bpermute_b32 v58, v59, v54
	ds_bpermute_b32 v59, v59, v55
	s_and_saveexec_b64 s[42:43], s[40:41]
	s_cbranch_execz .LBB0_516
	v_mov_b32_e32 v74, s53
	v_cndmask_b32_e64 v74, v66, v74, s[38:39]
	v_lshlrev_b32_e32 v75, 2, v3
	v_readlane_b32 s56, v254, 48
	v_lshl_or_b32 v74, v74, 5, v75
	v_mov_b32_e32 v75, v2
	v_readlane_b32 s60, v254, 52
	v_readlane_b32 s61, v254, 53
	v_readlane_b32 s57, v254, 49
	v_readlane_b32 s58, v254, 50
	v_lshl_add_u64 v[74:75], s[60:61], 0, v[74:75]
	v_add_co_u32_e32 v78, vcc, 0x2000, v74
	v_readlane_b32 s59, v254, 51
	s_nop 0
	v_addc_co_u32_e32 v79, vcc, 0, v75, vcc
	v_subrev_u32_e32 v130, s60, v78
	v_add_u32_e32 v130, 0xe000, v130
	ds_read_b128 v[74:77], v130 offset:2048
	s_nop 0
	ds_read_b128 v[78:81], v130
	v_readlane_b32 s62, v254, 54
	v_readlane_b32 s63, v254, 55
	s_waitcnt lgkmcnt(0)
	v_pk_mul_f32 v[62:63], v[74:75], v[62:63]
	v_pk_mul_f32 v[58:59], v[76:77], v[58:59]
	v_cndmask_b32_e64 v63, -v63, v63, s[36:37]
	v_cndmask_b32_e64 v59, -v59, v59, s[36:37]
	v_cndmask_b32_e64 v58, -v58, v58, s[36:37]
	v_cndmask_b32_e64 v62, -v62, v62, s[36:37]
	v_pk_fma_f32 v[54:55], v[54:55], v[80:81], v[58:59]
	v_pk_fma_f32 v[52:53], v[52:53], v[78:79], v[62:63]

.LBB0_517:
	s_movk_i32 s1, 0x600
	s_or_b32 s2, s46, 16
	s_waitcnt lgkmcnt(0)
	v_cvt_pk_bf16_f32 v58, v52, v53
	v_mad_i64_i32 v[52:53], s[20:21], v67, s1, v[64:65]
	s_mul_hi_i32 s3, s2, 0x2aaaaaab
	s_lshr_b32 s20, s3, 31
	s_lshr_b32 s3, s3, 4
	s_add_i32 s3, s3, s20
	s_mulk_i32 s3, 0x60
	s_sub_i32 s2, s2, s3
	s_cmp_gt_i32 s2, 63
	s_cselect_b64 s[40:41], -1, 0
	s_cmp_lt_i32 s2, 64
	s_mov_b32 s2, 0x3e16c740
	v_cvt_pk_bf16_f32 v59, v54, v55
	v_pk_mul_f32 v[50:51], v[50:51], s[2:3] op_sel_hi:[1,0]
	v_pk_mul_f32 v[48:49], v[48:49], s[2:3] op_sel_hi:[1,0]
	global_store_dwordx2 v[52:53], v[58:59], off
	s_cbranch_scc1 .LBB0_521
	v_cmp_lt_i32_e32 vcc, v180, v182
	s_movk_i32 s1, 0xfff
	s_nop 0
	v_cndmask_b32_e32 v54, v179, v180, vcc
	v_lshlrev_b32_e32 v55, 2, v54
	ds_bpermute_b32 v58, v55, v48
	ds_bpermute_b32 v59, v55, v49
	ds_bpermute_b32 v54, v55, v50
	ds_bpermute_b32 v55, v55, v51
	v_cmp_lt_i32_e32 vcc, s1, v71
	s_and_saveexec_b64 s[38:39], vcc
	s_cbranch_execz .LBB0_520
	v_lshlrev_b32_e32 v62, 2, v3
	v_readlane_b32 s56, v254, 48
	v_lshl_or_b32 v62, v70, 5, v62
	v_mov_b32_e32 v63, v2
	v_readlane_b32 s60, v254, 52
	v_readlane_b32 s61, v254, 53
	v_readlane_b32 s57, v254, 49
	v_readlane_b32 s58, v254, 50
	v_lshl_add_u64 v[62:63], s[60:61], 0, v[62:63]
	v_add_co_u32_e32 v74, vcc, 0x2000, v62
	v_readlane_b32 s59, v254, 51
	s_nop 0
	v_addc_co_u32_e32 v75, vcc, 0, v63, vcc
	v_subrev_u32_e32 v130, s60, v74
	v_add_u32_e32 v130, 0xe000, v130
	ds_read_b128 v[62:65], v130 offset:2048
	s_nop 0
	ds_read_b128 v[74:77], v130
	v_readlane_b32 s62, v254, 54
	v_readlane_b32 s63, v254, 55
	s_waitcnt lgkmcnt(0)
	v_pk_mul_f32 v[58:59], v[62:63], v[58:59]
	v_pk_mul_f32 v[54:55], v[64:65], v[54:55]
	v_cndmask_b32_e64 v59, -v59, v59, s[36:37]
	v_cndmask_b32_e64 v55, -v55, v55, s[36:37]
	v_cndmask_b32_e64 v54, -v54, v54, s[36:37]
	v_cndmask_b32_e64 v58, -v58, v58, s[36:37]
	v_pk_fma_f32 v[50:51], v[50:51], v[76:77], v[54:55]
	v_pk_fma_f32 v[48:49], v[48:49], v[74:75], v[58:59]

.LBB0_521:
	v_cvt_pk_bf16_f32 v48, v48, v49
	v_cvt_pk_bf16_f32 v49, v50, v51
	global_store_dwordx2 v[0:1], v[48:49], off offset:32
	v_cndmask_b32_e64 v48, 0, 1, s[40:41]
	v_pk_mul_f32 v[46:47], v[46:47], s[2:3] op_sel_hi:[1,0]
	v_cmp_ne_u32_e64 s[38:39], 1, v48
	s_andn2_b64 vcc, exec, s[40:41]
	v_pk_mul_f32 v[44:45], v[44:45], s[2:3] op_sel_hi:[1,0]
	s_cbranch_vccnz .LBB0_525
	v_cmp_lt_i32_e32 vcc, v180, v182
	s_movk_i32 s1, 0xfff
	s_nop 0
	v_cndmask_b32_e32 v48, v179, v180, vcc
	v_lshlrev_b32_e32 v49, 2, v48
	ds_bpermute_b32 v50, v49, v44
	ds_bpermute_b32 v51, v49, v45
	ds_bpermute_b32 v48, v49, v46
	ds_bpermute_b32 v49, v49, v47
	v_cmp_lt_i32_e32 vcc, s1, v73
	s_and_saveexec_b64 s[40:41], vcc
	s_cbranch_execz .LBB0_524
	s_waitcnt lgkmcnt(0)
	v_lshlrev_b32_e32 v54, 2, v3
	v_readlane_b32 s56, v254, 48
	v_lshl_or_b32 v54, v72, 5, v54
	v_mov_b32_e32 v55, v2
	v_readlane_b32 s60, v254, 52
	v_readlane_b32 s61, v254, 53
	v_readlane_b32 s57, v254, 49
	v_readlane_b32 s58, v254, 50
	v_lshl_add_u64 v[54:55], s[60:61], 0, v[54:55]
	v_add_co_u32_e32 v54, vcc, 0x2000, v54
	v_readlane_b32 s59, v254, 51
	s_nop 0
	v_addc_co_u32_e32 v55, vcc, 0, v55, vcc
	v_subrev_u32_e32 v130, s60, v54
	v_add_u32_e32 v130, 0xe000, v130
	ds_read_b128 v[62:65], v130 offset:2048
	ds_read_b128 v[74:77], v130
	v_readlane_b32 s62, v254, 54
	v_readlane_b32 s63, v254, 55
	s_waitcnt lgkmcnt(0)
	v_pk_mul_f32 v[50:51], v[62:63], v[50:51]
	v_pk_mul_f32 v[48:49], v[64:65], v[48:49]
	v_cndmask_b32_e64 v51, -v51, v51, s[36:37]
	v_cndmask_b32_e64 v49, -v49, v49, s[36:37]
	v_cndmask_b32_e64 v48, -v48, v48, s[36:37]
	v_cndmask_b32_e64 v50, -v50, v50, s[36:37]
	v_pk_fma_f32 v[46:47], v[46:47], v[76:77], v[48:49]
	v_pk_fma_f32 v[44:45], v[44:45], v[74:75], v[50:51]

.LBB0_525:
	v_cvt_pk_bf16_f32 v44, v44, v45
	v_cvt_pk_bf16_f32 v45, v46, v47
	v_pk_mul_f32 v[42:43], v[42:43], s[2:3] op_sel_hi:[1,0]
	s_and_b64 vcc, exec, s[38:39]
	v_pk_mul_f32 v[40:41], v[40:41], s[2:3] op_sel_hi:[1,0]
	global_store_dwordx2 v[60:61], v[44:45], off offset:32
	s_cbranch_vccnz .LBB0_529
	v_cmp_lt_i32_e32 vcc, v180, v182
	s_movk_i32 s1, 0xfff
	s_nop 0
	v_cndmask_b32_e32 v44, v179, v180, vcc
	v_lshlrev_b32_e32 v45, 2, v44
	ds_bpermute_b32 v46, v45, v40
	ds_bpermute_b32 v47, v45, v41
	ds_bpermute_b32 v44, v45, v42
	ds_bpermute_b32 v45, v45, v43
	v_cmp_lt_i32_e32 vcc, s1, v69
	s_and_saveexec_b64 s[40:41], vcc
	s_cbranch_execz .LBB0_528
	s_waitcnt lgkmcnt(0)
	v_lshlrev_b32_e32 v48, 2, v3
	v_readlane_b32 s56, v254, 48
	v_lshl_or_b32 v48, v68, 5, v48
	v_mov_b32_e32 v49, v2
	v_readlane_b32 s60, v254, 52
	v_readlane_b32 s61, v254, 53
	v_readlane_b32 s57, v254, 49
	v_readlane_b32 s58, v254, 50
	v_lshl_add_u64 v[48:49], s[60:61], 0, v[48:49]
	v_add_co_u32_e32 v54, vcc, 0x2000, v48
	v_readlane_b32 s59, v254, 51
	s_nop 0
	v_addc_co_u32_e32 v55, vcc, 0, v49, vcc
	v_subrev_u32_e32 v130, s60, v54
	v_add_u32_e32 v130, 0xe000, v130
	ds_read_b128 v[48:51], v130 offset:2048
	ds_read_b128 v[62:65], v130
	v_readlane_b32 s62, v254, 54
	v_readlane_b32 s63, v254, 55
	s_waitcnt lgkmcnt(0)
	v_pk_mul_f32 v[46:47], v[48:49], v[46:47]
	v_pk_mul_f32 v[44:45], v[50:51], v[44:45]
	v_cndmask_b32_e64 v47, -v47, v47, s[36:37]
	v_cndmask_b32_e64 v45, -v45, v45, s[36:37]
	v_cndmask_b32_e64 v44, -v44, v44, s[36:37]
	v_cndmask_b32_e64 v46, -v46, v46, s[36:37]
	v_pk_fma_f32 v[42:43], v[42:43], v[64:65], v[44:45]
	v_pk_fma_f32 v[40:41], v[40:41], v[62:63], v[46:47]

.LBB0_529:
	v_cvt_pk_bf16_f32 v40, v40, v41
	v_cvt_pk_bf16_f32 v41, v42, v43
	v_pk_mul_f32 v[38:39], v[38:39], s[2:3] op_sel_hi:[1,0]
	s_and_b64 vcc, exec, s[38:39]
	v_pk_mul_f32 v[36:37], v[36:37], s[2:3] op_sel_hi:[1,0]
	global_store_dwordx2 v[56:57], v[40:41], off offset:32
	s_cbranch_vccnz .LBB0_533
	v_cmp_lt_i32_e32 vcc, v180, v182
	s_movk_i32 s1, 0xfff
	s_nop 0
	v_cndmask_b32_e32 v40, v179, v180, vcc
	v_lshlrev_b32_e32 v41, 2, v40
	ds_bpermute_b32 v42, v41, v36
	ds_bpermute_b32 v43, v41, v37
	ds_bpermute_b32 v40, v41, v38
	ds_bpermute_b32 v41, v41, v39
	v_cmp_lt_i32_e32 vcc, s1, v67
	s_and_saveexec_b64 s[38:39], vcc
	s_cbranch_execz .LBB0_532
	s_waitcnt lgkmcnt(0)
	v_lshlrev_b32_e32 v44, 2, v3
	v_readlane_b32 s56, v254, 48
	v_lshl_or_b32 v44, v66, 5, v44
	v_mov_b32_e32 v45, v2
	v_readlane_b32 s60, v254, 52
	v_readlane_b32 s61, v254, 53
	v_readlane_b32 s57, v254, 49
	v_readlane_b32 s58, v254, 50
	v_lshl_add_u64 v[44:45], s[60:61], 0, v[44:45]
	v_add_co_u32_e32 v48, vcc, 0x2000, v44
	v_readlane_b32 s59, v254, 51
	s_nop 0
	v_addc_co_u32_e32 v49, vcc, 0, v45, vcc
	v_subrev_u32_e32 v130, s60, v48
	v_add_u32_e32 v130, 0xe000, v130
	ds_read_b128 v[44:47], v130 offset:2048
	s_nop 0
	ds_read_b128 v[48:51], v130
	v_readlane_b32 s62, v254, 54
	v_readlane_b32 s63, v254, 55
	s_waitcnt lgkmcnt(0)
	v_pk_mul_f32 v[42:43], v[44:45], v[42:43]
	v_pk_mul_f32 v[40:41], v[46:47], v[40:41]
	v_cndmask_b32_e64 v43, -v43, v43, s[36:37]
	v_cndmask_b32_e64 v41, -v41, v41, s[36:37]
	v_cndmask_b32_e64 v40, -v40, v40, s[36:37]
	v_cndmask_b32_e64 v42, -v42, v42, s[36:37]
	v_pk_fma_f32 v[38:39], v[38:39], v[50:51], v[40:41]
	v_pk_fma_f32 v[36:37], v[36:37], v[48:49], v[42:43]

.LBB0_533:
	s_or_b32 s2, s46, 32
	s_mul_hi_i32 s3, s2, 0x2aaaaaab
	s_lshr_b32 s20, s3, 31
	s_lshr_b32 s3, s3, 4
	s_add_i32 s3, s3, s20
	s_mulk_i32 s3, 0x60
	s_sub_i32 s2, s2, s3
	s_cmp_gt_i32 s2, 63
	s_cselect_b64 s[42:43], -1, 0
	s_cmp_eq_u32 s2, 64
	s_cselect_b64 s[38:39], -1, 0
	s_cmp_lt_i32 s2, 64
	s_mov_b32 s2, 0x3e16c740
	v_cvt_pk_bf16_f32 v36, v36, v37
	v_cvt_pk_bf16_f32 v37, v38, v39
	v_pk_mul_f32 v[34:35], v[34:35], s[2:3] op_sel_hi:[1,0]
	v_pk_mul_f32 v[32:33], v[32:33], s[2:3] op_sel_hi:[1,0]
	global_store_dwordx2 v[52:53], v[36:37], off offset:32
	s_cbranch_scc1 .LBB0_537
	v_cmp_lt_i32_e32 vcc, v180, v182
	s_movk_i32 s1, 0xfff
	s_nop 0
	v_cndmask_b32_e32 v36, v179, v180, vcc
	v_lshlrev_b32_e32 v37, 2, v36
	ds_bpermute_b32 v38, v37, v32
	ds_bpermute_b32 v39, v37, v33
	ds_bpermute_b32 v36, v37, v34
	ds_bpermute_b32 v37, v37, v35
	v_cmp_lt_i32_e32 vcc, s1, v71
	s_and_saveexec_b64 s[40:41], vcc
	s_cbranch_execz .LBB0_536
	s_waitcnt lgkmcnt(0)
	v_mov_b32_e32 v40, s53
	v_cndmask_b32_e64 v40, v70, v40, s[38:39]
	v_lshlrev_b32_e32 v41, 2, v3
	v_readlane_b32 s56, v254, 48
	v_lshl_or_b32 v40, v40, 5, v41
	v_mov_b32_e32 v41, v2
	v_readlane_b32 s60, v254, 52
	v_readlane_b32 s61, v254, 53
	v_readlane_b32 s57, v254, 49
	v_readlane_b32 s58, v254, 50
	v_lshl_add_u64 v[40:41], s[60:61], 0, v[40:41]
	v_add_co_u32_e32 v44, vcc, 0x2000, v40
	v_readlane_b32 s59, v254, 51
	s_nop 0
	v_addc_co_u32_e32 v45, vcc, 0, v41, vcc
	v_subrev_u32_e32 v130, s60, v44
	v_add_u32_e32 v130, 0xe000, v130
	ds_read_b128 v[40:43], v130 offset:2048
	s_nop 0
	ds_read_b128 v[44:47], v130
	v_readlane_b32 s62, v254, 54
	v_readlane_b32 s63, v254, 55
	s_waitcnt lgkmcnt(0)
	v_pk_mul_f32 v[38:39], v[40:41], v[38:39]
	v_pk_mul_f32 v[36:37], v[42:43], v[36:37]
	v_cndmask_b32_e64 v39, -v39, v39, s[36:37]
	v_cndmask_b32_e64 v37, -v37, v37, s[36:37]
	v_cndmask_b32_e64 v36, -v36, v36, s[36:37]
	v_cndmask_b32_e64 v38, -v38, v38, s[36:37]
	v_pk_fma_f32 v[34:35], v[34:35], v[46:47], v[36:37]
	v_pk_fma_f32 v[32:33], v[32:33], v[44:45], v[38:39]

.LBB0_537:
	v_cvt_pk_bf16_f32 v32, v32, v33
	v_cvt_pk_bf16_f32 v33, v34, v35
	global_store_dwordx2 v[0:1], v[32:33], off offset:64
	v_cndmask_b32_e64 v32, 0, 1, s[42:43]
	v_pk_mul_f32 v[30:31], v[30:31], s[2:3] op_sel_hi:[1,0]
	v_cmp_ne_u32_e64 s[40:41], 1, v32
	s_andn2_b64 vcc, exec, s[42:43]
	v_pk_mul_f32 v[28:29], v[28:29], s[2:3] op_sel_hi:[1,0]
	s_cbranch_vccnz .LBB0_541
	v_cmp_lt_i32_e32 vcc, v180, v182
	s_movk_i32 s1, 0xfff
	s_nop 0
	v_cndmask_b32_e32 v32, v179, v180, vcc
	v_lshlrev_b32_e32 v33, 2, v32
	ds_bpermute_b32 v34, v33, v28
	ds_bpermute_b32 v35, v33, v29
	ds_bpermute_b32 v32, v33, v30
	ds_bpermute_b32 v33, v33, v31
	v_cmp_lt_i32_e32 vcc, s1, v73
	s_and_saveexec_b64 s[42:43], vcc
	s_cbranch_execz .LBB0_540
	s_waitcnt lgkmcnt(0)
	v_mov_b32_e32 v36, s53
	v_cndmask_b32_e64 v36, v72, v36, s[38:39]
	v_lshlrev_b32_e32 v37, 2, v3
	v_readlane_b32 s56, v254, 48
	v_lshl_or_b32 v36, v36, 5, v37
	v_mov_b32_e32 v37, v2
	v_readlane_b32 s60, v254, 52
	v_readlane_b32 s61, v254, 53
	v_readlane_b32 s57, v254, 49
	v_readlane_b32 s58, v254, 50
	v_lshl_add_u64 v[36:37], s[60:61], 0, v[36:37]
	v_add_co_u32_e32 v40, vcc, 0x2000, v36
	v_readlane_b32 s59, v254, 51
	s_nop 0
	v_addc_co_u32_e32 v41, vcc, 0, v37, vcc
	v_subrev_u32_e32 v130, s60, v40
	v_add_u32_e32 v130, 0xe000, v130
	ds_read_b128 v[36:39], v130 offset:2048
	s_nop 0
	ds_read_b128 v[40:43], v130
	v_readlane_b32 s62, v254, 54
	v_readlane_b32 s63, v254, 55
	s_waitcnt lgkmcnt(0)
	v_pk_mul_f32 v[34:35], v[36:37], v[34:35]
	v_pk_mul_f32 v[32:33], v[38:39], v[32:33]
	v_cndmask_b32_e64 v35, -v35, v35, s[36:37]
	v_cndmask_b32_e64 v33, -v33, v33, s[36:37]
	v_cndmask_b32_e64 v32, -v32, v32, s[36:37]
	v_cndmask_b32_e64 v34, -v34, v34, s[36:37]
	v_pk_fma_f32 v[30:31], v[30:31], v[42:43], v[32:33]
	v_pk_fma_f32 v[28:29], v[28:29], v[40:41], v[34:35]

.LBB0_541:
	v_cvt_pk_bf16_f32 v28, v28, v29
	v_cvt_pk_bf16_f32 v29, v30, v31
	v_pk_mul_f32 v[26:27], v[26:27], s[2:3] op_sel_hi:[1,0]
	s_and_b64 vcc, exec, s[40:41]
	v_pk_mul_f32 v[24:25], v[24:25], s[2:3] op_sel_hi:[1,0]
	global_store_dwordx2 v[60:61], v[28:29], off offset:64
	s_cbranch_vccnz .LBB0_545
	v_cmp_lt_i32_e32 vcc, v180, v182
	s_movk_i32 s1, 0xfff
	s_nop 0
	v_cndmask_b32_e32 v28, v179, v180, vcc
	v_lshlrev_b32_e32 v29, 2, v28
	ds_bpermute_b32 v30, v29, v24
	ds_bpermute_b32 v31, v29, v25
	ds_bpermute_b32 v28, v29, v26
	ds_bpermute_b32 v29, v29, v27
	v_cmp_lt_i32_e32 vcc, s1, v69
	s_and_saveexec_b64 s[42:43], vcc
	s_cbranch_execz .LBB0_544
	s_waitcnt lgkmcnt(0)
	v_mov_b32_e32 v32, s53
	v_cndmask_b32_e64 v32, v68, v32, s[38:39]
	v_lshlrev_b32_e32 v33, 2, v3
	v_readlane_b32 s56, v254, 48
	v_lshl_or_b32 v32, v32, 5, v33
	v_mov_b32_e32 v33, v2
	v_readlane_b32 s60, v254, 52
	v_readlane_b32 s61, v254, 53
	v_readlane_b32 s57, v254, 49
	v_readlane_b32 s58, v254, 50
	v_lshl_add_u64 v[32:33], s[60:61], 0, v[32:33]
	v_add_co_u32_e32 v36, vcc, 0x2000, v32
	v_readlane_b32 s59, v254, 51
	s_nop 0
	v_addc_co_u32_e32 v37, vcc, 0, v33, vcc
	v_subrev_u32_e32 v130, s60, v36
	v_add_u32_e32 v130, 0xe000, v130
	ds_read_b128 v[32:35], v130 offset:2048
	s_nop 0
	ds_read_b128 v[36:39], v130
	v_readlane_b32 s62, v254, 54
	v_readlane_b32 s63, v254, 55
	s_waitcnt lgkmcnt(0)
	v_pk_mul_f32 v[30:31], v[32:33], v[30:31]
	v_pk_mul_f32 v[28:29], v[34:35], v[28:29]
	v_cndmask_b32_e64 v31, -v31, v31, s[36:37]
	v_cndmask_b32_e64 v29, -v29, v29, s[36:37]
	v_cndmask_b32_e64 v28, -v28, v28, s[36:37]
	v_cndmask_b32_e64 v30, -v30, v30, s[36:37]
	v_pk_fma_f32 v[26:27], v[26:27], v[38:39], v[28:29]
	v_pk_fma_f32 v[24:25], v[24:25], v[36:37], v[30:31]

.LBB0_545:
	v_cvt_pk_bf16_f32 v24, v24, v25
	v_cvt_pk_bf16_f32 v25, v26, v27
	v_pk_mul_f32 v[22:23], v[22:23], s[2:3] op_sel_hi:[1,0]
	s_and_b64 vcc, exec, s[40:41]
	v_pk_mul_f32 v[20:21], v[20:21], s[2:3] op_sel_hi:[1,0]
	global_store_dwordx2 v[56:57], v[24:25], off offset:64
	s_cbranch_vccnz .LBB0_549
	v_cmp_lt_i32_e32 vcc, v180, v182
	s_movk_i32 s1, 0xfff
	s_nop 0
	v_cndmask_b32_e32 v24, v179, v180, vcc
	v_lshlrev_b32_e32 v25, 2, v24
	ds_bpermute_b32 v26, v25, v20
	ds_bpermute_b32 v27, v25, v21
	ds_bpermute_b32 v24, v25, v22
	ds_bpermute_b32 v25, v25, v23
	v_cmp_lt_i32_e32 vcc, s1, v67
	s_and_saveexec_b64 s[40:41], vcc
	s_cbranch_execz .LBB0_548
	s_waitcnt lgkmcnt(0)
	v_mov_b32_e32 v28, s53
	v_cndmask_b32_e64 v28, v66, v28, s[38:39]
	v_lshlrev_b32_e32 v29, 2, v3
	v_readlane_b32 s56, v254, 48
	v_lshl_or_b32 v28, v28, 5, v29
	v_mov_b32_e32 v29, v2
	v_readlane_b32 s60, v254, 52
	v_readlane_b32 s61, v254, 53
	v_readlane_b32 s57, v254, 49
	v_readlane_b32 s58, v254, 50
	v_lshl_add_u64 v[28:29], s[60:61], 0, v[28:29]
	v_add_co_u32_e32 v32, vcc, 0x2000, v28
	v_readlane_b32 s59, v254, 51
	s_nop 0
	v_addc_co_u32_e32 v33, vcc, 0, v29, vcc
	v_subrev_u32_e32 v130, s60, v32
	v_add_u32_e32 v130, 0xe000, v130
	ds_read_b128 v[28:31], v130 offset:2048
	s_nop 0
	ds_read_b128 v[32:35], v130
	v_readlane_b32 s62, v254, 54
	v_readlane_b32 s63, v254, 55
	s_waitcnt lgkmcnt(0)
	v_pk_mul_f32 v[26:27], v[28:29], v[26:27]
	v_pk_mul_f32 v[24:25], v[30:31], v[24:25]
	v_cndmask_b32_e64 v27, -v27, v27, s[36:37]
	v_cndmask_b32_e64 v25, -v25, v25, s[36:37]
	v_cndmask_b32_e64 v24, -v24, v24, s[36:37]
	v_cndmask_b32_e64 v26, -v26, v26, s[36:37]
	v_pk_fma_f32 v[22:23], v[22:23], v[34:35], v[24:25]
	v_pk_fma_f32 v[20:21], v[20:21], v[32:33], v[26:27]

.LBB0_549:
	s_or_b32 s2, s46, 48
	s_mul_hi_i32 s3, s2, 0x2aaaaaab
	s_lshr_b32 s20, s3, 31
	s_lshr_b32 s3, s3, 4
	s_add_i32 s3, s3, s20
	s_mulk_i32 s3, 0x60
	s_sub_i32 s2, s2, s3
	s_cmp_gt_i32 s2, 63
	s_cselect_b64 s[40:41], -1, 0
	s_cmp_lt_i32 s2, 64
	s_mov_b32 s2, 0x3e16c740
	v_cvt_pk_bf16_f32 v20, v20, v21
	v_cvt_pk_bf16_f32 v21, v22, v23
	v_pk_mul_f32 v[18:19], v[18:19], s[2:3] op_sel_hi:[1,0]
	v_pk_mul_f32 v[16:17], v[16:17], s[2:3] op_sel_hi:[1,0]
	global_store_dwordx2 v[52:53], v[20:21], off offset:64
	s_cbranch_scc1 .LBB0_553
	v_cmp_lt_i32_e32 vcc, v180, v182
	s_movk_i32 s1, 0xfff
	s_nop 0
	v_cndmask_b32_e32 v20, v179, v180, vcc
	v_lshlrev_b32_e32 v21, 2, v20
	ds_bpermute_b32 v22, v21, v16
	ds_bpermute_b32 v23, v21, v17
	ds_bpermute_b32 v20, v21, v18
	ds_bpermute_b32 v21, v21, v19
	v_cmp_lt_i32_e32 vcc, s1, v71
	s_and_saveexec_b64 s[38:39], vcc
	s_cbranch_execz .LBB0_552
	s_waitcnt lgkmcnt(0)
	v_lshlrev_b32_e32 v24, 2, v3
	v_readlane_b32 s56, v254, 48
	v_lshl_or_b32 v24, v70, 5, v24
	v_mov_b32_e32 v25, v2
	v_readlane_b32 s60, v254, 52
	v_readlane_b32 s61, v254, 53
	v_readlane_b32 s57, v254, 49
	v_readlane_b32 s58, v254, 50
	v_lshl_add_u64 v[24:25], s[60:61], 0, v[24:25]
	v_add_co_u32_e32 v28, vcc, 0x2000, v24
	v_readlane_b32 s59, v254, 51
	s_nop 0
	v_addc_co_u32_e32 v29, vcc, 0, v25, vcc
	v_subrev_u32_e32 v130, s60, v28
	v_add_u32_e32 v130, 0xe000, v130
	ds_read_b128 v[24:27], v130 offset:2048
	s_nop 0
	ds_read_b128 v[28:31], v130
	v_readlane_b32 s62, v254, 54
	v_readlane_b32 s63, v254, 55
	s_waitcnt lgkmcnt(0)
	v_pk_mul_f32 v[22:23], v[24:25], v[22:23]
	v_pk_mul_f32 v[20:21], v[26:27], v[20:21]
	v_cndmask_b32_e64 v23, -v23, v23, s[36:37]
	v_cndmask_b32_e64 v21, -v21, v21, s[36:37]
	v_cndmask_b32_e64 v20, -v20, v20, s[36:37]
	v_cndmask_b32_e64 v22, -v22, v22, s[36:37]
	v_pk_fma_f32 v[18:19], v[18:19], v[30:31], v[20:21]
	v_pk_fma_f32 v[16:17], v[16:17], v[28:29], v[22:23]

.LBB0_553:
	v_cvt_pk_bf16_f32 v16, v16, v17
	v_cvt_pk_bf16_f32 v17, v18, v19
	global_store_dwordx2 v[0:1], v[16:17], off offset:96
	v_pk_mul_f32 v[0:1], v[14:15], s[2:3] op_sel_hi:[1,0]
	v_cndmask_b32_e64 v14, 0, 1, s[40:41]
	v_cmp_ne_u32_e64 s[38:39], 1, v14
	s_andn2_b64 vcc, exec, s[40:41]
	v_pk_mul_f32 v[12:13], v[12:13], s[2:3] op_sel_hi:[1,0]
	s_cbranch_vccnz .LBB0_557
	v_cmp_lt_i32_e32 vcc, v180, v182
	s_movk_i32 s1, 0xfff
	s_nop 0
	v_cndmask_b32_e32 v14, v179, v180, vcc
	v_lshlrev_b32_e32 v15, 2, v14
	ds_bpermute_b32 v16, v15, v12
	ds_bpermute_b32 v17, v15, v13
	ds_bpermute_b32 v14, v15, v0
	ds_bpermute_b32 v15, v15, v1
	v_cmp_lt_i32_e32 vcc, s1, v73
	s_and_saveexec_b64 s[40:41], vcc
	s_cbranch_execz .LBB0_556
	v_lshlrev_b32_e32 v18, 2, v3
	v_readlane_b32 s56, v254, 48
	v_lshl_or_b32 v18, v72, 5, v18
	v_mov_b32_e32 v19, v2
	v_readlane_b32 s60, v254, 52
	v_readlane_b32 s61, v254, 53
	v_readlane_b32 s57, v254, 49
	v_readlane_b32 s58, v254, 50
	v_lshl_add_u64 v[18:19], s[60:61], 0, v[18:19]
	s_waitcnt lgkmcnt(0)
	v_add_co_u32_e32 v22, vcc, 0x2000, v18
	v_readlane_b32 s59, v254, 51
	s_nop 0
	v_addc_co_u32_e32 v23, vcc, 0, v19, vcc
	v_subrev_u32_e32 v130, s60, v22
	v_add_u32_e32 v130, 0xe000, v130
	ds_read_b128 v[18:21], v130 offset:2048
	s_nop 0
	ds_read_b128 v[22:25], v130
	v_readlane_b32 s62, v254, 54
	v_readlane_b32 s63, v254, 55
	s_waitcnt lgkmcnt(0)
	v_pk_mul_f32 v[16:17], v[18:19], v[16:17]
	v_pk_mul_f32 v[14:15], v[20:21], v[14:15]
	v_cndmask_b32_e64 v17, -v17, v17, s[36:37]
	v_cndmask_b32_e64 v15, -v15, v15, s[36:37]
	v_cndmask_b32_e64 v14, -v14, v14, s[36:37]
	v_cndmask_b32_e64 v16, -v16, v16, s[36:37]
	v_pk_fma_f32 v[0:1], v[0:1], v[24:25], v[14:15]
	v_pk_fma_f32 v[12:13], v[12:13], v[22:23], v[16:17]

.LBB0_557:
	v_cvt_pk_bf16_f32 v12, v12, v13
	v_cvt_pk_bf16_f32 v13, v0, v1
	v_pk_mul_f32 v[0:1], v[10:11], s[2:3] op_sel_hi:[1,0]
	s_and_b64 vcc, exec, s[38:39]
	v_pk_mul_f32 v[8:9], v[8:9], s[2:3] op_sel_hi:[1,0]
	global_store_dwordx2 v[60:61], v[12:13], off offset:96
	s_cbranch_vccnz .LBB0_561
	v_cmp_lt_i32_e32 vcc, v180, v182
	s_movk_i32 s1, 0xfff
	s_nop 0
	v_cndmask_b32_e32 v10, v179, v180, vcc
	v_lshlrev_b32_e32 v11, 2, v10
	ds_bpermute_b32 v12, v11, v8
	ds_bpermute_b32 v13, v11, v9
	ds_bpermute_b32 v10, v11, v0
	ds_bpermute_b32 v11, v11, v1
	v_cmp_lt_i32_e32 vcc, s1, v69
	s_and_saveexec_b64 s[40:41], vcc
	s_cbranch_execz .LBB0_560
	s_waitcnt lgkmcnt(0)
	v_lshlrev_b32_e32 v14, 2, v3
	v_readlane_b32 s56, v254, 48
	v_lshl_or_b32 v14, v68, 5, v14
	v_mov_b32_e32 v15, v2
	v_readlane_b32 s60, v254, 52
	v_readlane_b32 s61, v254, 53
	v_readlane_b32 s57, v254, 49
	v_readlane_b32 s58, v254, 50
	v_lshl_add_u64 v[14:15], s[60:61], 0, v[14:15]
	v_add_co_u32_e32 v18, vcc, 0x2000, v14
	v_readlane_b32 s59, v254, 51
	s_nop 0
	v_addc_co_u32_e32 v19, vcc, 0, v15, vcc
	v_subrev_u32_e32 v130, s60, v18
	v_add_u32_e32 v130, 0xe000, v130
	ds_read_b128 v[14:17], v130 offset:2048
	s_nop 0
	ds_read_b128 v[18:21], v130
	v_readlane_b32 s62, v254, 54
	v_readlane_b32 s63, v254, 55
	s_waitcnt lgkmcnt(0)
	v_pk_mul_f32 v[12:13], v[14:15], v[12:13]
	v_pk_mul_f32 v[10:11], v[16:17], v[10:11]
	v_cndmask_b32_e64 v13, -v13, v13, s[36:37]
	v_cndmask_b32_e64 v11, -v11, v11, s[36:37]
	v_cndmask_b32_e64 v10, -v10, v10, s[36:37]
	v_cndmask_b32_e64 v12, -v12, v12, s[36:37]
	v_pk_fma_f32 v[0:1], v[0:1], v[20:21], v[10:11]
	v_pk_fma_f32 v[8:9], v[8:9], v[18:19], v[12:13]

.LBB0_561:
	v_cvt_pk_bf16_f32 v8, v8, v9
	v_cvt_pk_bf16_f32 v9, v0, v1
	v_pk_mul_f32 v[0:1], v[6:7], s[2:3] op_sel_hi:[1,0]
	s_and_b64 vcc, exec, s[38:39]
	v_pk_mul_f32 v[4:5], v[4:5], s[2:3] op_sel_hi:[1,0]
	global_store_dwordx2 v[56:57], v[8:9], off offset:96
	s_cbranch_vccnz .LBB0_492
	v_cmp_lt_i32_e32 vcc, v180, v182
	s_movk_i32 s1, 0xfff
	s_nop 0
	v_cndmask_b32_e32 v6, v179, v180, vcc
	v_lshlrev_b32_e32 v7, 2, v6
	ds_bpermute_b32 v8, v7, v4
	ds_bpermute_b32 v9, v7, v5
	ds_bpermute_b32 v6, v7, v0
	ds_bpermute_b32 v7, v7, v1
	v_cmp_lt_i32_e32 vcc, s1, v67
	s_and_saveexec_b64 s[38:39], vcc
	s_cbranch_execz .LBB0_491
	v_lshlrev_b32_e32 v3, 2, v3
	v_readlane_b32 s56, v254, 48
	s_waitcnt lgkmcnt(0)
	v_lshl_or_b32 v10, v66, 5, v3
	v_mov_b32_e32 v11, v2
	v_readlane_b32 s60, v254, 52
	v_readlane_b32 s61, v254, 53
	v_readlane_b32 s57, v254, 49
	v_readlane_b32 s58, v254, 50
	v_lshl_add_u64 v[10:11], s[60:61], 0, v[10:11]
	v_add_co_u32_e32 v14, vcc, 0x2000, v10
	v_readlane_b32 s59, v254, 51
	s_nop 0
	v_addc_co_u32_e32 v15, vcc, 0, v11, vcc
	v_subrev_u32_e32 v130, s60, v14
	v_add_u32_e32 v130, 0xe000, v130
	ds_read_b128 v[10:13], v130 offset:2048
	s_nop 0
	ds_read_b128 v[14:17], v130
	v_readlane_b32 s62, v254, 54
	v_readlane_b32 s63, v254, 55
	s_waitcnt lgkmcnt(0)
	v_pk_mul_f32 v[8:9], v[10:11], v[8:9]
	v_pk_mul_f32 v[6:7], v[12:13], v[6:7]
	v_cndmask_b32_e64 v9, -v9, v9, s[36:37]
	v_cndmask_b32_e64 v7, -v7, v7, s[36:37]
	v_cndmask_b32_e64 v6, -v6, v6, s[36:37]
	v_cndmask_b32_e64 v8, -v8, v8, s[36:37]
	v_pk_fma_f32 v[0:1], v[0:1], v[16:17], v[6:7]
	v_pk_fma_f32 v[4:5], v[4:5], v[14:15], v[8:9]
	s_branch .LBB0_491
